# stack: deferred Griffin cg waits + ssin-from-LDS in IN0/IN1 epilogues + Griffin gate->scan block barrier removed (wave-local)
# baseline (speedup 1.0000x reference)
.LBB0_523:
	s_or_b64 exec, exec, s[28:29]
	s_waitcnt lgkmcnt(0)
	ds_read_b128 v[66:69], v148 offset:33424
	ds_read_b128 v[72:75], v237 offset:42640
	ds_read_b128 v[76:79], v148 offset:33488
	ds_read_b128 v[80:83], v237 offset:42704
	ds_read_b128 v[84:87], v237 offset:44944
	ds_read_b128 v[88:91], v237 offset:45008
	s_waitcnt lgkmcnt(4)
	v_mfma_f32_16x16x32_bf16 v[72:75], v[66:69], v[72:75], 0
	s_waitcnt lgkmcnt(1)
	v_mfma_f32_16x16x32_bf16 v[66:69], v[66:69], v[84:87], 0
	v_add_u32_e32 v84, 0x5000, v155
	v_mfma_f32_16x16x32_bf16 v[72:75], v[76:79], v[80:83], v[72:75]
	v_lshlrev_b32_e32 v80, 4, v71
	v_mad_u64_u32 v[82:83], s[28:29], v70, s44, v[80:81]
	s_waitcnt lgkmcnt(0)
	v_mfma_f32_16x16x32_bf16 v[66:69], v[76:79], v[88:91], v[66:69]
	s_nop 7
	ds_write2_b32 v84, v72, v66 offset0:32 offset1:48
	ds_write2_b32 v84, v73, v67 offset0:65 offset1:81
	ds_write2_b32 v84, v74, v68 offset0:98 offset1:114
	ds_write2_b32 v84, v75, v69 offset0:131 offset1:147
	s_waitcnt lgkmcnt(0)
	ds_read_b32 v78, v80 offset:9600
	v_add_u32_e32 v68, 0x5080, v82
	v_add_u32_e32 v71, 0x50c0, v82
	v_mad_u64_u32 v[66:67], s[28:29], v70, s33, v[80:81]
	v_add_u32_e32 v74, 0x5088, v82
	v_add_u32_e32 v67, 0x7180, v66
	ds_read2_b32 v[68:69], v68 offset1:1
	ds_read2_b32 v[70:71], v71 offset1:1
	ds_read2_b32 v[72:73], v67 offset1:1
	ds_read2_b32 v[74:75], v74 offset1:1
	v_add_u32_e32 v67, 0x7188, v66
	ds_read_b32 v79, v80 offset:9664
	ds_read2_b32 v[76:77], v67 offset1:1
	s_waitcnt lgkmcnt(5)
	v_add_f32_e32 v67, v68, v78
	v_mul_f32_e32 v67, 0xbfb8aa3b, v67
	v_exp_f32_e32 v67, v67
	ds_read_b32 v68, v80 offset:9728
	s_waitcnt lgkmcnt(2)
	v_add_f32_e32 v70, v70, v79
	v_mul_f32_e32 v70, 0xbfb8aa3b, v70
	v_add_f32_e32 v67, 1.0, v67
	v_rcp_f32_e32 v67, v67
	v_exp_f32_e32 v70, v70
	v_mul_f32_e32 v67, 0xc1000000, v67
	s_waitcnt lgkmcnt(0)
	v_mul_f32_e32 v67, v68, v67
	v_mul_f32_e32 v67, 0x3fb8aa3b, v67
	v_exp_f32_e32 v67, v67
	v_add_f32_e32 v68, 1.0, v70
	v_rcp_f32_e32 v68, v68
	v_fma_f32 v70, -v67, v67, 1.0
	v_max_f32_e32 v70, 0, v70
	v_sqrt_f32_e32 v70, v70
	v_mul_f32_e32 v68, v72, v68
	v_mul_f32_e32 v68, v68, v70
	ds_write_b32 v66, v67 offset:9792
	ds_write_b32 v66, v68 offset:14144
	ds_read_b32 v67, v80 offset:9604
	ds_read_b32 v68, v80 offset:9668
	ds_read_b32 v70, v80 offset:9732
	s_waitcnt lgkmcnt(2)
	v_add_f32_e32 v67, v69, v67
	v_mul_f32_e32 v67, 0xbfb8aa3b, v67
	v_exp_f32_e32 v67, v67
	s_waitcnt lgkmcnt(1)
	v_add_f32_e32 v68, v71, v68
	v_mul_f32_e32 v68, 0xbfb8aa3b, v68
	v_exp_f32_e32 v68, v68
	v_add_f32_e32 v67, 1.0, v67
	v_rcp_f32_e32 v67, v67
	v_add_f32_e32 v68, 1.0, v68
	v_rcp_f32_e32 v68, v68
	v_mul_f32_e32 v67, 0xc1000000, v67
	s_waitcnt lgkmcnt(0)
	v_mul_f32_e32 v67, v70, v67
	v_mul_f32_e32 v67, 0x3fb8aa3b, v67
	v_exp_f32_e32 v67, v67
	v_mul_f32_e32 v68, v73, v68
	v_fma_f32 v69, -v67, v67, 1.0
	v_max_f32_e32 v69, 0, v69
	v_sqrt_f32_e32 v69, v69
	ds_write_b32 v66, v67 offset:9796
	v_mul_f32_e32 v67, v68, v69
	ds_write_b32 v66, v67 offset:14148
	ds_read_b32 v67, v80 offset:9608
	v_add_u32_e32 v68, 0x50c8, v82
	ds_read_b32 v70, v80 offset:9672
	ds_read_b32 v71, v80 offset:9736
	ds_read2_b32 v[68:69], v68 offset1:1
	s_waitcnt lgkmcnt(3)
	v_add_f32_e32 v67, v74, v67
	v_mul_f32_e32 v67, 0xbfb8aa3b, v67
	v_exp_f32_e32 v67, v67
	s_waitcnt lgkmcnt(0)
	v_add_f32_e32 v68, v68, v70
	v_mul_f32_e32 v68, 0xbfb8aa3b, v68
	v_exp_f32_e32 v68, v68
	v_add_f32_e32 v67, 1.0, v67
	v_rcp_f32_e32 v67, v67
	v_add_u32_e32 v74, 64, v230
	v_add_f32_e32 v68, 1.0, v68
	v_rcp_f32_e32 v68, v68
	v_mul_f32_e32 v67, 0xc1000000, v67
	v_mul_f32_e32 v67, v71, v67
	v_mul_f32_e32 v67, 0x3fb8aa3b, v67
	v_exp_f32_e32 v67, v67
	v_mul_f32_e32 v68, v76, v68
	v_add_u32_e32 v71, 0x3400, v240
	v_fma_f32 v70, -v67, v67, 1.0
	v_max_f32_e32 v70, 0, v70
	v_sqrt_f32_e32 v70, v70
	ds_write_b32 v66, v67 offset:9800
	v_mul_f32_e32 v67, v68, v70
	ds_write_b32 v66, v67 offset:14152
	ds_read_b32 v67, v80 offset:9612
	ds_read_b32 v68, v80 offset:9676
	ds_read_b32 v70, v80 offset:9740
	s_waitcnt lgkmcnt(2)
	v_add_f32_e32 v67, v75, v67
	v_mul_f32_e32 v67, 0xbfb8aa3b, v67
	v_exp_f32_e32 v67, v67
	s_waitcnt lgkmcnt(1)
	v_add_f32_e32 v68, v69, v68
	v_mul_f32_e32 v68, 0xbfb8aa3b, v68
	v_exp_f32_e32 v68, v68
	v_add_f32_e32 v67, 1.0, v67
	v_rcp_f32_e32 v67, v67
	v_add_f32_e32 v68, 1.0, v68
	v_rcp_f32_e32 v68, v68
	v_mul_f32_e32 v67, 0xc1000000, v67
	s_waitcnt lgkmcnt(0)
	v_mul_f32_e32 v67, v70, v67
	v_mul_f32_e32 v67, 0x3fb8aa3b, v67
	v_exp_f32_e32 v67, v67
	v_mul_f32_e32 v68, v77, v68
	v_add_u32_e32 v70, 0x2400, v240
	v_fma_f32 v69, -v67, v67, 1.0
	v_max_f32_e32 v69, 0, v69
	v_sqrt_f32_e32 v69, v69
	ds_write_b32 v66, v67 offset:9804
	v_mul_f32_e32 v67, v68, v69
	ds_write_b32 v66, v67 offset:14156
	s_waitcnt lgkmcnt(0)
	ds_read2_b32 v[72:73], v70 offset0:144 offset1:161
	ds_read2_b32 v[68:69], v71 offset0:208 offset1:225
	v_add_u32_e32 v66, 0x3600, v240
	ds_read2_b32 v[70:71], v70 offset0:178 offset1:195
	ds_read2_b32 v[66:67], v66 offset0:114 offset1:131
	s_waitcnt lgkmcnt(3)
	v_mul_f32_e32 v76, v72, v73
	s_waitcnt lgkmcnt(2)
	v_fma_f32 v75, 0, v72, v68
	v_fma_f32 v75, v75, v73, v69
	s_waitcnt lgkmcnt(1)
	v_mul_f32_e32 v76, v76, v70
	s_waitcnt lgkmcnt(0)
	v_fma_f32 v75, v75, v70, v66
	v_mul_f32_e32 v76, v76, v71
	v_fma_f32 v75, v75, v71, v67
	ds_write2st64_b32 v74, v76, v75 offset0:72 offset1:76
	s_waitcnt lgkmcnt(0)
	s_barrier
	ds_read_b32 v74, v239 offset:20544
	ds_read2st64_b32 v[80:81], v241 offset1:4
	v_add_u32_e32 v76, 64, v241
	ds_read2st64_b32 v[82:83], v76 offset1:4
	v_add_u32_e32 v75, 128, v241
	ds_read2st64_b32 v[84:85], v75 offset1:4
	v_add_u32_e32 v76, 192, v241
	ds_read2st64_b32 v[86:87], v76 offset1:4
	v_add_u32_e32 v75, 256, v241
	ds_read2st64_b32 v[88:89], v75 offset1:4
	v_add_u32_e32 v76, 320, v241
	ds_read2st64_b32 v[90:91], v76 offset1:4
	v_add_u32_e32 v75, 384, v241
	ds_read2st64_b32 v[92:93], v75 offset1:4
	v_add_u32_e32 v76, 448, v241
	ds_read2st64_b32 v[94:95], v76 offset1:4
	v_add_u32_e32 v75, 512, v241
	ds_read2st64_b32 v[96:97], v75 offset1:4
	v_add_u32_e32 v76, 576, v241
	ds_read2st64_b32 v[98:99], v76 offset1:4
	s_waitcnt lgkmcnt(6)
	v_add_u32_e32 v75, 640, v241
	ds_read2st64_b32 v[100:101], v75 offset1:4
	v_add_u32_e32 v76, 704, v241
	ds_read2st64_b32 v[102:103], v76 offset1:4
	v_add_u32_e32 v75, 768, v241
	ds_read2st64_b32 v[104:105], v75 offset1:4
	v_add_u32_e32 v76, 832, v241
	ds_read2st64_b32 v[106:107], v76 offset1:4
	v_add_u32_e32 v75, 896, v241
	ds_read2st64_b32 v[108:109], v75 offset1:4
	s_mov_b64 s[28:29], exec
	s_waitcnt lgkmcnt(0)
	v_cmpx_lt_u32_e32 vcc, 0, v233
	v_fma_f32 v74, v80, v74, v81
	v_cmpx_lt_u32_e32 vcc, 1, v233
	v_fma_f32 v74, v82, v74, v83
	v_cmpx_lt_u32_e32 vcc, 2, v233
	v_fma_f32 v74, v84, v74, v85
	v_cmpx_lt_u32_e32 vcc, 3, v233
	v_fma_f32 v74, v86, v74, v87
	v_cmpx_lt_u32_e32 vcc, 4, v233
	v_fma_f32 v74, v88, v74, v89
	v_cmpx_lt_u32_e32 vcc, 5, v233
	v_fma_f32 v74, v90, v74, v91
	v_cmpx_lt_u32_e32 vcc, 6, v233
	v_fma_f32 v74, v92, v74, v93
	v_cmpx_lt_u32_e32 vcc, 7, v233
	v_fma_f32 v74, v94, v74, v95
	v_cmpx_lt_u32_e32 vcc, 8, v233
	v_fma_f32 v74, v96, v74, v97
	v_cmpx_lt_u32_e32 vcc, 9, v233
	v_fma_f32 v74, v98, v74, v99
	v_cmpx_lt_u32_e32 vcc, 10, v233
	v_fma_f32 v74, v100, v74, v101
	v_cmpx_lt_u32_e32 vcc, 11, v233
	v_fma_f32 v74, v102, v74, v103
	v_cmpx_lt_u32_e32 vcc, 12, v233
	v_fma_f32 v74, v104, v74, v105
	v_cmpx_lt_u32_e32 vcc, 13, v233
	v_fma_f32 v74, v106, v74, v107
	v_cmpx_lt_u32_e32 vcc, 14, v233
	v_fma_f32 v74, v108, v74, v109
	s_mov_b64 exec, s[28:29]
